# grid barriers 2..13: per-XCD arrival kept, the last arriver of each XCD writes L2 back and arrives at the top counter, which every workgroup polls directly (no generation-word hops)
# baseline (speedup 1.0000x reference)
; #define LAS __attribute__((address_space(3)))
; __device__ __forceinline__ unsigned xb_ld(unsigned* p)              { return __hip_atomic_load(p, __ATOMIC_RELAXED, __HIP_MEMORY_SCOPE_AGENT); }
; __device__ __forceinline__ unsigned xb_xcc_id() { return (unsigned)__builtin_amdgcn_s_getreg((3 << 11) | 20) & 0xFu; }
; __device__ __forceinline__ void xb_census(unsigned* bar, volatile LAS unsigned* st) {
;   const unsigned x = xb_xcc_id();
;   unsigned cnt = 0u, mine = 1u;
; #pragma unroll 1
;   for (unsigned j = 0; j < 16; ++j) { const unsigned c = xb_ld(&bar[XB_XCNT(j)]); cnt += (c > 0u) ? 1u : 0u; if (j == x) mine = c; }
;   st[0] = mine > 0u ? mine : 1u; st[1] = cnt > 0u ? cnt : 1u; st[2] = x;
; }
.LBB0_243:
	s_or_b64 exec, exec, s[10:11]
	v_readlane_b32 s84, v253, 46
	s_cmp_lt_i32 s75, 1
	s_mov_b64 s[96:97], s[36:37]
	s_mov_b64 s[42:43], s[90:91]
	v_readlane_b32 s85, v253, 47
	s_cbranch_scc1 .LBB0_259
	v_lshrrev_b32_e32 v1, 20, v0
	v_lshrrev_b32_e32 v2, 10, v0
	v_or_b32_e32 v1, v2, v1
	s_movk_i32 s0, 0x3ff
	v_and_or_b32 v1, v1, s0, v192
	v_cmp_eq_u32_e32 vcc, 0, v1
	s_barrier
	s_and_saveexec_b64 s[4:5], vcc
	s_cbranch_execz .LBB0_254
	buffer_wbl2 sc1
	s_waitcnt vmcnt(0)
	s_load_dword s8, s[96:97], 0xb0
	v_mov_b32_e32 v3, 0
	v_mov_b32_e32 v4, 1
	s_add_u32 s6, s72, 0x19008400
	s_addc_u32 s7, s73, 0
	s_mov_b32 s10, 0
	global_atomic_add v3, v4, s[6:7] offset:16
	s_waitcnt lgkmcnt(0)
	v_mov_b32_e32 v1, 0x2010c
	v_mov_b32_e32 v2, s8
	ds_write_b32 v1, v2

; #define LAS __attribute__((address_space(3)))
; __device__ __forceinline__ unsigned xb_ld(unsigned* p)              { return __hip_atomic_load(p, __ATOMIC_RELAXED, __HIP_MEMORY_SCOPE_AGENT); }
; __device__ __forceinline__ unsigned xb_add(unsigned* p, unsigned v) { return __hip_atomic_fetch_add(p, v, __ATOMIC_RELAXED, __HIP_MEMORY_SCOPE_AGENT); }
; #define XB_SPIN(cond) do { unsigned _sp = 0; while (cond) { __builtin_amdgcn_s_sleep(1); if (++_sp > (1u << 24)) break; } } while (0)
; __device__ __forceinline__ void grid_barrier(unsigned* bar, volatile LAS unsigned* st, unsigned k) {
;   asm volatile("s_waitcnt vmcnt(0)" ::: "memory");
;   __syncthreads();
;   if (threadIdx.x == 0) {
;     __builtin_amdgcn_s_waitcnt(0);
;     const unsigned nloc = st[0], nx = st[1], x = st[2];
;     const unsigned old = xb_add(&bar[XB_XSUB(x)], 1u);
;     if (old + 1u == (k + 1u) * nloc) {
;       __builtin_amdgcn_fence(__ATOMIC_RELEASE, "agent");
;       asm volatile("s_waitcnt vmcnt(0)" ::: "memory");
;       const unsigned og = xb_add(&bar[XB_TOP], 1u);
;       if (og + 1u == (k + 1u) * nx) xb_add(&bar[XB_TOPGEN], 1u);
;       else XB_SPIN(xb_ld(&bar[XB_TOPGEN]) == k);
;       __builtin_amdgcn_fence(__ATOMIC_ACQUIRE, "agent");
;       xb_add(&bar[XB_XGEN(x)], 1u);
;       asm volatile("s_waitcnt vmcnt(0)" ::: "memory");
;     } else {
;       XB_SPIN(xb_ld(&bar[XB_XGEN(x)]) == k);
;       __builtin_amdgcn_fence(__ATOMIC_ACQUIRE, "agent");
;       asm volatile("s_waitcnt vmcnt(0)" ::: "memory");
;     }
;   }
;   __syncthreads();
; }
.LBB0_342:
	s_cmp_lt_i32 s75, 3
	s_cbranch_scc1 .LBB0_386
	s_waitcnt vmcnt(0)
	s_add_i32 s0, s33, 1
	s_waitcnt vmcnt(0) lgkmcnt(0)
	s_barrier
	s_mov_b64 s[4:5], exec
	v_readlane_b32 s6, v253, 0
	v_readlane_b32 s7, v253, 1
	s_and_b64 s[6:7], s[4:5], s[6:7]
	s_mov_b64 exec, s[6:7]
	s_cbranch_execz .LBB0_385
	v_mov_b32_e32 v0, 0x20100
	ds_read_b32 v1, v0
	ds_read_b32 v2, v0 offset:4
	ds_read_b32 v3, v0 offset:8
	s_add_u32 s6, s72, 0x19009800
	s_addc_u32 s7, s73, 0
	v_mov_b32_e32 v0, 0
	v_mov_b32_e32 v4, 1
	s_add_i32 s8, s33, 1
	s_waitcnt vmcnt(0) lgkmcnt(0)
	v_readfirstlane_b32 s9, v1
	v_readfirstlane_b32 s10, v2
	v_readfirstlane_b32 vcc_lo, v3
	s_mul_i32 s9, s9, s8
	s_mul_i32 s10, s10, s8
	s_lshl_b32 s8, vcc_lo, 8
	s_add_u32 s6, s6, s8
	s_addc_u32 s7, s7, 0
	global_atomic_add v1, v0, v4, s[6:7] sc0
	s_add_u32 s6, s72, 0x1900b800
	s_addc_u32 s7, s73, 0
	s_mov_b32 vcc_lo, 0
	s_waitcnt vmcnt(0)
	v_readfirstlane_b32 s8, v1
	s_add_i32 s8, s8, 1
	s_cmp_lg_u32 s8, s9
	s_cbranch_scc1 .Llb1_spin
	buffer_wbl2 sc1
	s_waitcnt vmcnt(0)
	global_atomic_add v0, v4, s[6:7]
.Llb1_spin:
	global_load_dword v1, v0, s[6:7] sc1
	s_add_u32 vcc_lo, vcc_lo, 1
	s_waitcnt vmcnt(0)
	v_readfirstlane_b32 s8, v1
	s_cmp_ge_u32 vcc_lo, 0x400000
	s_cbranch_scc1 .Llb1_done
	s_cmp_ge_u32 s8, s10
	s_cbranch_scc1 .Llb1_done
	s_sleep 1
	s_branch .Llb1_spin
.Llb1_done:
	buffer_inv sc1
	s_waitcnt vmcnt(0)
.LBB0_385:
	s_or_b64 exec, exec, s[4:5]
	s_mov_b32 s33, s0
	s_barrier

; #define LAS __attribute__((address_space(3)))
; __device__ __forceinline__ unsigned xb_ld(unsigned* p)              { return __hip_atomic_load(p, __ATOMIC_RELAXED, __HIP_MEMORY_SCOPE_AGENT); }
; __device__ __forceinline__ unsigned xb_add(unsigned* p, unsigned v) { return __hip_atomic_fetch_add(p, v, __ATOMIC_RELAXED, __HIP_MEMORY_SCOPE_AGENT); }
; #define XB_SPIN(cond) do { unsigned _sp = 0; while (cond) { __builtin_amdgcn_s_sleep(1); if (++_sp > (1u << 24)) break; } } while (0)
; __device__ __forceinline__ void grid_barrier(unsigned* bar, volatile LAS unsigned* st, unsigned k) {
;   asm volatile("s_waitcnt vmcnt(0)" ::: "memory");
;   __syncthreads();
;   if (threadIdx.x == 0) {
;     __builtin_amdgcn_s_waitcnt(0);
;     const unsigned nloc = st[0], nx = st[1], x = st[2];
;     const unsigned old = xb_add(&bar[XB_XSUB(x)], 1u);
;     if (old + 1u == (k + 1u) * nloc) {
;       __builtin_amdgcn_fence(__ATOMIC_RELEASE, "agent");
;       asm volatile("s_waitcnt vmcnt(0)" ::: "memory");
;       const unsigned og = xb_add(&bar[XB_TOP], 1u);
;       if (og + 1u == (k + 1u) * nx) xb_add(&bar[XB_TOPGEN], 1u);
;       else XB_SPIN(xb_ld(&bar[XB_TOPGEN]) == k);
;       __builtin_amdgcn_fence(__ATOMIC_ACQUIRE, "agent");
;       xb_add(&bar[XB_XGEN(x)], 1u);
;       asm volatile("s_waitcnt vmcnt(0)" ::: "memory");
;     } else {
;       XB_SPIN(xb_ld(&bar[XB_XGEN(x)]) == k);
;       __builtin_amdgcn_fence(__ATOMIC_ACQUIRE, "agent");
;       asm volatile("s_waitcnt vmcnt(0)" ::: "memory");
;     }
;   }
;   __syncthreads();
; }
.LBB0_426:
	s_waitcnt vmcnt(0)
	s_add_i32 s0, s33, 1
	s_waitcnt vmcnt(0) lgkmcnt(0)
	s_barrier
	s_mov_b64 s[4:5], exec
	v_readlane_b32 s6, v253, 0
	v_readlane_b32 s7, v253, 1
	s_and_b64 s[6:7], s[4:5], s[6:7]
	s_mov_b64 exec, s[6:7]
	s_cbranch_execz .LBB0_468
	v_mov_b32_e32 v0, 0x20100
	ds_read_b32 v1, v0
	ds_read_b32 v2, v0 offset:4
	ds_read_b32 v3, v0 offset:8
	s_add_u32 s6, s72, 0x19009800
	s_addc_u32 s7, s73, 0
	v_mov_b32_e32 v0, 0
	v_mov_b32_e32 v4, 1
	s_add_i32 s8, s33, 1
	s_waitcnt vmcnt(0) lgkmcnt(0)
	v_readfirstlane_b32 s9, v1
	v_readfirstlane_b32 s10, v2
	v_readfirstlane_b32 vcc_lo, v3
	s_mul_i32 s9, s9, s8
	s_mul_i32 s10, s10, s8
	s_lshl_b32 s8, vcc_lo, 8
	s_add_u32 s6, s6, s8
	s_addc_u32 s7, s7, 0
	global_atomic_add v1, v0, v4, s[6:7] sc0
	s_add_u32 s6, s72, 0x1900b800
	s_addc_u32 s7, s73, 0
	s_mov_b32 vcc_lo, 0
	s_waitcnt vmcnt(0)
	v_readfirstlane_b32 s8, v1
	s_add_i32 s8, s8, 1
	s_cmp_lg_u32 s8, s9
	s_cbranch_scc1 .Llb2_spin
	buffer_wbl2 sc1
	s_waitcnt vmcnt(0)
	global_atomic_add v0, v4, s[6:7]

; #define LAS __attribute__((address_space(3)))
; __device__ __forceinline__ unsigned xb_ld(unsigned* p)              { return __hip_atomic_load(p, __ATOMIC_RELAXED, __HIP_MEMORY_SCOPE_AGENT); }
; __device__ __forceinline__ unsigned xb_add(unsigned* p, unsigned v) { return __hip_atomic_fetch_add(p, v, __ATOMIC_RELAXED, __HIP_MEMORY_SCOPE_AGENT); }
; #define XB_SPIN(cond) do { unsigned _sp = 0; while (cond) { __builtin_amdgcn_s_sleep(1); if (++_sp > (1u << 24)) break; } } while (0)
; __device__ __forceinline__ void grid_barrier(unsigned* bar, volatile LAS unsigned* st, unsigned k) {
;   asm volatile("s_waitcnt vmcnt(0)" ::: "memory");
;   __syncthreads();
;   if (threadIdx.x == 0) {
;     __builtin_amdgcn_s_waitcnt(0);
;     const unsigned nloc = st[0], nx = st[1], x = st[2];
;     const unsigned old = xb_add(&bar[XB_XSUB(x)], 1u);
;     if (old + 1u == (k + 1u) * nloc) {
;       __builtin_amdgcn_fence(__ATOMIC_RELEASE, "agent");
;       asm volatile("s_waitcnt vmcnt(0)" ::: "memory");
;       const unsigned og = xb_add(&bar[XB_TOP], 1u);
;       if (og + 1u == (k + 1u) * nx) xb_add(&bar[XB_TOPGEN], 1u);
;       else XB_SPIN(xb_ld(&bar[XB_TOPGEN]) == k);
;       __builtin_amdgcn_fence(__ATOMIC_ACQUIRE, "agent");
;       xb_add(&bar[XB_XGEN(x)], 1u);
;       asm volatile("s_waitcnt vmcnt(0)" ::: "memory");
;     } else {
;       XB_SPIN(xb_ld(&bar[XB_XGEN(x)]) == k);
;       __builtin_amdgcn_fence(__ATOMIC_ACQUIRE, "agent");
;       asm volatile("s_waitcnt vmcnt(0)" ::: "memory");
;     }
;   }
;   __syncthreads();
; }
.Llb2_done:
	buffer_inv sc1
	s_waitcnt vmcnt(0)
.LBB0_468:
	s_or_b64 exec, exec, s[4:5]
	s_mov_b32 s33, s0
	s_barrier

; #define LAS __attribute__((address_space(3)))
; __device__ __forceinline__ unsigned xb_ld(unsigned* p)              { return __hip_atomic_load(p, __ATOMIC_RELAXED, __HIP_MEMORY_SCOPE_AGENT); }
; __device__ __forceinline__ unsigned xb_add(unsigned* p, unsigned v) { return __hip_atomic_fetch_add(p, v, __ATOMIC_RELAXED, __HIP_MEMORY_SCOPE_AGENT); }
; #define XB_SPIN(cond) do { unsigned _sp = 0; while (cond) { __builtin_amdgcn_s_sleep(1); if (++_sp > (1u << 24)) break; } } while (0)
; __device__ __forceinline__ void grid_barrier(unsigned* bar, volatile LAS unsigned* st, unsigned k) {
;   asm volatile("s_waitcnt vmcnt(0)" ::: "memory");
;   __syncthreads();
;   if (threadIdx.x == 0) {
;     __builtin_amdgcn_s_waitcnt(0);
;     const unsigned nloc = st[0], nx = st[1], x = st[2];
;     const unsigned old = xb_add(&bar[XB_XSUB(x)], 1u);
;     if (old + 1u == (k + 1u) * nloc) {
;       __builtin_amdgcn_fence(__ATOMIC_RELEASE, "agent");
;       asm volatile("s_waitcnt vmcnt(0)" ::: "memory");
;       const unsigned og = xb_add(&bar[XB_TOP], 1u);
;       if (og + 1u == (k + 1u) * nx) xb_add(&bar[XB_TOPGEN], 1u);
;       else XB_SPIN(xb_ld(&bar[XB_TOPGEN]) == k);
;       __builtin_amdgcn_fence(__ATOMIC_ACQUIRE, "agent");
;       xb_add(&bar[XB_XGEN(x)], 1u);
;       asm volatile("s_waitcnt vmcnt(0)" ::: "memory");
;     } else {
;       XB_SPIN(xb_ld(&bar[XB_XGEN(x)]) == k);
;       __builtin_amdgcn_fence(__ATOMIC_ACQUIRE, "agent");
;       asm volatile("s_waitcnt vmcnt(0)" ::: "memory");
;     }
;   }
;   __syncthreads();
; }
.Llb3_done:
	buffer_inv sc1
	s_waitcnt vmcnt(0)
.LBB0_559:
	s_or_b64 exec, exec, s[4:5]
	s_mov_b32 s33, s0
	s_barrier

; #define LAS __attribute__((address_space(3)))
; __device__ __forceinline__ unsigned xb_ld(unsigned* p)              { return __hip_atomic_load(p, __ATOMIC_RELAXED, __HIP_MEMORY_SCOPE_AGENT); }
; __device__ __forceinline__ unsigned xb_add(unsigned* p, unsigned v) { return __hip_atomic_fetch_add(p, v, __ATOMIC_RELAXED, __HIP_MEMORY_SCOPE_AGENT); }
; #define XB_SPIN(cond) do { unsigned _sp = 0; while (cond) { __builtin_amdgcn_s_sleep(1); if (++_sp > (1u << 24)) break; } } while (0)
; __device__ __forceinline__ void grid_barrier(unsigned* bar, volatile LAS unsigned* st, unsigned k) {
;   asm volatile("s_waitcnt vmcnt(0)" ::: "memory");
;   __syncthreads();
;   if (threadIdx.x == 0) {
;     __builtin_amdgcn_s_waitcnt(0);
;     const unsigned nloc = st[0], nx = st[1], x = st[2];
;     const unsigned old = xb_add(&bar[XB_XSUB(x)], 1u);
;     if (old + 1u == (k + 1u) * nloc) {
;       __builtin_amdgcn_fence(__ATOMIC_RELEASE, "agent");
;       asm volatile("s_waitcnt vmcnt(0)" ::: "memory");
;       const unsigned og = xb_add(&bar[XB_TOP], 1u);
;       if (og + 1u == (k + 1u) * nx) xb_add(&bar[XB_TOPGEN], 1u);
;       else XB_SPIN(xb_ld(&bar[XB_TOPGEN]) == k);
;       __builtin_amdgcn_fence(__ATOMIC_ACQUIRE, "agent");
;       xb_add(&bar[XB_XGEN(x)], 1u);
;       asm volatile("s_waitcnt vmcnt(0)" ::: "memory");
;     } else {
;       XB_SPIN(xb_ld(&bar[XB_XGEN(x)]) == k);
;       __builtin_amdgcn_fence(__ATOMIC_ACQUIRE, "agent");
;       asm volatile("s_waitcnt vmcnt(0)" ::: "memory");
;     }
;   }
;   __syncthreads();
; }
.LBB0_564:
	s_or_b64 exec, exec, s[10:11]
	v_readlane_b32 s14, v253, 22
	s_cmp_lt_u32 s75, 7
	v_readlane_b32 s15, v253, 23
	s_mov_b64 s[42:43], s[44:45]
	s_cbranch_scc1 .LBB0_609
	s_waitcnt vmcnt(0)
	s_add_i32 s0, s33, 1
	s_waitcnt vmcnt(0) lgkmcnt(0)
	s_barrier
	s_mov_b64 s[4:5], exec
	v_readlane_b32 s6, v253, 0
	v_readlane_b32 s7, v253, 1
	s_and_b64 s[6:7], s[4:5], s[6:7]
	s_mov_b64 exec, s[6:7]
	s_cbranch_execz .LBB0_608
	v_mov_b32_e32 v0, 0x20100
	ds_read_b32 v1, v0
	ds_read_b32 v2, v0 offset:4
	ds_read_b32 v3, v0 offset:8
	s_add_u32 s6, s72, 0x19009800
	s_addc_u32 s7, s73, 0
	v_mov_b32_e32 v0, 0
	v_mov_b32_e32 v4, 1
	s_add_i32 s8, s33, 1
	s_waitcnt vmcnt(0) lgkmcnt(0)
	v_readfirstlane_b32 s9, v1
	v_readfirstlane_b32 s10, v2
	v_readfirstlane_b32 vcc_lo, v3
	s_mul_i32 s9, s9, s8
	s_mul_i32 s10, s10, s8
	s_lshl_b32 s8, vcc_lo, 8
	s_add_u32 s6, s6, s8
	s_addc_u32 s7, s7, 0
	global_atomic_add v1, v0, v4, s[6:7] sc0
	s_add_u32 s6, s72, 0x1900b800
	s_addc_u32 s7, s73, 0
	s_mov_b32 vcc_lo, 0
	s_waitcnt vmcnt(0)
	v_readfirstlane_b32 s8, v1
	s_add_i32 s8, s8, 1
	s_cmp_lg_u32 s8, s9
	s_cbranch_scc1 .Llb4_spin
	buffer_wbl2 sc1
	s_waitcnt vmcnt(0)
	global_atomic_add v0, v4, s[6:7]

; #define LAS __attribute__((address_space(3)))
; __device__ __forceinline__ unsigned xb_ld(unsigned* p)              { return __hip_atomic_load(p, __ATOMIC_RELAXED, __HIP_MEMORY_SCOPE_AGENT); }
; __device__ __forceinline__ unsigned xb_add(unsigned* p, unsigned v) { return __hip_atomic_fetch_add(p, v, __ATOMIC_RELAXED, __HIP_MEMORY_SCOPE_AGENT); }
; #define XB_SPIN(cond) do { unsigned _sp = 0; while (cond) { __builtin_amdgcn_s_sleep(1); if (++_sp > (1u << 24)) break; } } while (0)
; __device__ __forceinline__ void grid_barrier(unsigned* bar, volatile LAS unsigned* st, unsigned k) {
;   asm volatile("s_waitcnt vmcnt(0)" ::: "memory");
;   __syncthreads();
;   if (threadIdx.x == 0) {
;     __builtin_amdgcn_s_waitcnt(0);
;     const unsigned nloc = st[0], nx = st[1], x = st[2];
;     const unsigned old = xb_add(&bar[XB_XSUB(x)], 1u);
;     if (old + 1u == (k + 1u) * nloc) {
;       __builtin_amdgcn_fence(__ATOMIC_RELEASE, "agent");
;       asm volatile("s_waitcnt vmcnt(0)" ::: "memory");
;       const unsigned og = xb_add(&bar[XB_TOP], 1u);
;       if (og + 1u == (k + 1u) * nx) xb_add(&bar[XB_TOPGEN], 1u);
;       else XB_SPIN(xb_ld(&bar[XB_TOPGEN]) == k);
;       __builtin_amdgcn_fence(__ATOMIC_ACQUIRE, "agent");
;       xb_add(&bar[XB_XGEN(x)], 1u);
;       asm volatile("s_waitcnt vmcnt(0)" ::: "memory");
;     } else {
;       XB_SPIN(xb_ld(&bar[XB_XGEN(x)]) == k);
;       __builtin_amdgcn_fence(__ATOMIC_ACQUIRE, "agent");
;       asm volatile("s_waitcnt vmcnt(0)" ::: "memory");
;     }
;   }
;   __syncthreads();
; }
.Llb4_done:
	buffer_inv sc1
	s_waitcnt vmcnt(0)
	s_branch .LBB0_608
.LBB0_570:
	v_readlane_b32 s14, v253, 22
	v_readlane_b32 s15, v253, 23
	s_branch .LBB0_609
.LBB0_608:
	s_or_b64 exec, exec, s[4:5]
	s_barrier
	s_mov_b32 s33, s0

; #define LAS __attribute__((address_space(3)))
; __device__ __forceinline__ unsigned xb_ld(unsigned* p)              { return __hip_atomic_load(p, __ATOMIC_RELAXED, __HIP_MEMORY_SCOPE_AGENT); }
; __device__ __forceinline__ unsigned xb_add(unsigned* p, unsigned v) { return __hip_atomic_fetch_add(p, v, __ATOMIC_RELAXED, __HIP_MEMORY_SCOPE_AGENT); }
; #define XB_SPIN(cond) do { unsigned _sp = 0; while (cond) { __builtin_amdgcn_s_sleep(1); if (++_sp > (1u << 24)) break; } } while (0)
; __device__ __forceinline__ void grid_barrier(unsigned* bar, volatile LAS unsigned* st, unsigned k) {
;   asm volatile("s_waitcnt vmcnt(0)" ::: "memory");
;   __syncthreads();
;   if (threadIdx.x == 0) {
;     __builtin_amdgcn_s_waitcnt(0);
;     const unsigned nloc = st[0], nx = st[1], x = st[2];
;     const unsigned old = xb_add(&bar[XB_XSUB(x)], 1u);
;     if (old + 1u == (k + 1u) * nloc) {
;       __builtin_amdgcn_fence(__ATOMIC_RELEASE, "agent");
;       asm volatile("s_waitcnt vmcnt(0)" ::: "memory");
;       const unsigned og = xb_add(&bar[XB_TOP], 1u);
;       if (og + 1u == (k + 1u) * nx) xb_add(&bar[XB_TOPGEN], 1u);
;       else XB_SPIN(xb_ld(&bar[XB_TOPGEN]) == k);
;       __builtin_amdgcn_fence(__ATOMIC_ACQUIRE, "agent");
;       xb_add(&bar[XB_XGEN(x)], 1u);
;       asm volatile("s_waitcnt vmcnt(0)" ::: "memory");
;     } else {
;       XB_SPIN(xb_ld(&bar[XB_XGEN(x)]) == k);
;       __builtin_amdgcn_fence(__ATOMIC_ACQUIRE, "agent");
;       asm volatile("s_waitcnt vmcnt(0)" ::: "memory");
;     }
;   }
;   __syncthreads();
; }
.Llb5_done:
	buffer_inv sc1
	s_waitcnt vmcnt(0)
.LBB0_695:
	s_or_b64 exec, exec, s[4:5]
	s_mov_b32 s33, s0
	s_barrier

; #define LAS __attribute__((address_space(3)))
; __device__ __forceinline__ unsigned xb_ld(unsigned* p)              { return __hip_atomic_load(p, __ATOMIC_RELAXED, __HIP_MEMORY_SCOPE_AGENT); }
; __device__ __forceinline__ unsigned xb_add(unsigned* p, unsigned v) { return __hip_atomic_fetch_add(p, v, __ATOMIC_RELAXED, __HIP_MEMORY_SCOPE_AGENT); }
; #define XB_SPIN(cond) do { unsigned _sp = 0; while (cond) { __builtin_amdgcn_s_sleep(1); if (++_sp > (1u << 24)) break; } } while (0)
; __device__ __forceinline__ void grid_barrier(unsigned* bar, volatile LAS unsigned* st, unsigned k) {
;   asm volatile("s_waitcnt vmcnt(0)" ::: "memory");
;   __syncthreads();
;   if (threadIdx.x == 0) {
;     __builtin_amdgcn_s_waitcnt(0);
;     const unsigned nloc = st[0], nx = st[1], x = st[2];
;     const unsigned old = xb_add(&bar[XB_XSUB(x)], 1u);
;     if (old + 1u == (k + 1u) * nloc) {
;       __builtin_amdgcn_fence(__ATOMIC_RELEASE, "agent");
;       asm volatile("s_waitcnt vmcnt(0)" ::: "memory");
;       const unsigned og = xb_add(&bar[XB_TOP], 1u);
;       if (og + 1u == (k + 1u) * nx) xb_add(&bar[XB_TOPGEN], 1u);
;       else XB_SPIN(xb_ld(&bar[XB_TOPGEN]) == k);
;       __builtin_amdgcn_fence(__ATOMIC_ACQUIRE, "agent");
;       xb_add(&bar[XB_XGEN(x)], 1u);
;       asm volatile("s_waitcnt vmcnt(0)" ::: "memory");
;     } else {
;       XB_SPIN(xb_ld(&bar[XB_XGEN(x)]) == k);
;       __builtin_amdgcn_fence(__ATOMIC_ACQUIRE, "agent");
;       asm volatile("s_waitcnt vmcnt(0)" ::: "memory");
;     }
;   }
;   __syncthreads();
; }
.Llb6_done:
	buffer_inv sc1
	s_waitcnt vmcnt(0)
.LBB0_890:
	s_or_b64 exec, exec, s[4:5]
	s_mov_b32 s33, s0
	s_barrier

; #define LAS __attribute__((address_space(3)))
; __device__ __forceinline__ unsigned xb_ld(unsigned* p)              { return __hip_atomic_load(p, __ATOMIC_RELAXED, __HIP_MEMORY_SCOPE_AGENT); }
; __device__ __forceinline__ unsigned xb_add(unsigned* p, unsigned v) { return __hip_atomic_fetch_add(p, v, __ATOMIC_RELAXED, __HIP_MEMORY_SCOPE_AGENT); }
; #define XB_SPIN(cond) do { unsigned _sp = 0; while (cond) { __builtin_amdgcn_s_sleep(1); if (++_sp > (1u << 24)) break; } } while (0)
; __device__ __forceinline__ void grid_barrier(unsigned* bar, volatile LAS unsigned* st, unsigned k) {
;   asm volatile("s_waitcnt vmcnt(0)" ::: "memory");
;   __syncthreads();
;   if (threadIdx.x == 0) {
;     __builtin_amdgcn_s_waitcnt(0);
;     const unsigned nloc = st[0], nx = st[1], x = st[2];
;     const unsigned old = xb_add(&bar[XB_XSUB(x)], 1u);
;     if (old + 1u == (k + 1u) * nloc) {
;       __builtin_amdgcn_fence(__ATOMIC_RELEASE, "agent");
;       asm volatile("s_waitcnt vmcnt(0)" ::: "memory");
;       const unsigned og = xb_add(&bar[XB_TOP], 1u);
;       if (og + 1u == (k + 1u) * nx) xb_add(&bar[XB_TOPGEN], 1u);
;       else XB_SPIN(xb_ld(&bar[XB_TOPGEN]) == k);
;       __builtin_amdgcn_fence(__ATOMIC_ACQUIRE, "agent");
;       xb_add(&bar[XB_XGEN(x)], 1u);
;       asm volatile("s_waitcnt vmcnt(0)" ::: "memory");
;     } else {
;       XB_SPIN(xb_ld(&bar[XB_XGEN(x)]) == k);
;       __builtin_amdgcn_fence(__ATOMIC_ACQUIRE, "agent");
;       asm volatile("s_waitcnt vmcnt(0)" ::: "memory");
;     }
;   }
;   __syncthreads();
; }
.LBB0_1173:
	s_cmp_lt_i32 s75, 14
	s_cbranch_scc1 .LBB0_1217
	s_waitcnt vmcnt(0)
	s_add_i32 s0, s33, 1
	s_waitcnt vmcnt(0) lgkmcnt(0)
	s_barrier
	s_mov_b64 s[4:5], exec
	v_readlane_b32 s6, v253, 0
	v_readlane_b32 s7, v253, 1
	s_and_b64 s[6:7], s[4:5], s[6:7]
	s_mov_b64 exec, s[6:7]
	s_cbranch_execz .LBB0_1216
	v_mov_b32_e32 v0, 0x20100
	ds_read_b32 v1, v0
	ds_read_b32 v2, v0 offset:4
	ds_read_b32 v3, v0 offset:8
	s_add_u32 s6, s72, 0x19009800
	s_addc_u32 s7, s73, 0
	v_mov_b32_e32 v0, 0
	v_mov_b32_e32 v4, 1
	s_add_i32 s8, s33, 1
	s_waitcnt vmcnt(0) lgkmcnt(0)
	v_readfirstlane_b32 s9, v1
	v_readfirstlane_b32 s10, v2
	v_readfirstlane_b32 vcc_lo, v3
	s_mul_i32 s9, s9, s8
	s_mul_i32 s10, s10, s8
	s_lshl_b32 s8, vcc_lo, 8
	s_add_u32 s6, s6, s8
	s_addc_u32 s7, s7, 0
	global_atomic_add v1, v0, v4, s[6:7] sc0
	s_add_u32 s6, s72, 0x1900b800
	s_addc_u32 s7, s73, 0
	s_mov_b32 vcc_lo, 0
	s_waitcnt vmcnt(0)
	v_readfirstlane_b32 s8, v1
	s_add_i32 s8, s8, 1
	s_cmp_lg_u32 s8, s9
	s_cbranch_scc1 .Llb7_spin
	buffer_wbl2 sc1
	s_waitcnt vmcnt(0)
	global_atomic_add v0, v4, s[6:7]

; #define LAS __attribute__((address_space(3)))
; __device__ __forceinline__ unsigned xb_ld(unsigned* p)              { return __hip_atomic_load(p, __ATOMIC_RELAXED, __HIP_MEMORY_SCOPE_AGENT); }
; __device__ __forceinline__ unsigned xb_add(unsigned* p, unsigned v) { return __hip_atomic_fetch_add(p, v, __ATOMIC_RELAXED, __HIP_MEMORY_SCOPE_AGENT); }
; #define XB_SPIN(cond) do { unsigned _sp = 0; while (cond) { __builtin_amdgcn_s_sleep(1); if (++_sp > (1u << 24)) break; } } while (0)
; __device__ __forceinline__ void grid_barrier(unsigned* bar, volatile LAS unsigned* st, unsigned k) {
;   asm volatile("s_waitcnt vmcnt(0)" ::: "memory");
;   __syncthreads();
;   if (threadIdx.x == 0) {
;     __builtin_amdgcn_s_waitcnt(0);
;     const unsigned nloc = st[0], nx = st[1], x = st[2];
;     const unsigned old = xb_add(&bar[XB_XSUB(x)], 1u);
;     if (old + 1u == (k + 1u) * nloc) {
;       __builtin_amdgcn_fence(__ATOMIC_RELEASE, "agent");
;       asm volatile("s_waitcnt vmcnt(0)" ::: "memory");
;       const unsigned og = xb_add(&bar[XB_TOP], 1u);
;       if (og + 1u == (k + 1u) * nx) xb_add(&bar[XB_TOPGEN], 1u);
;       else XB_SPIN(xb_ld(&bar[XB_TOPGEN]) == k);
;       __builtin_amdgcn_fence(__ATOMIC_ACQUIRE, "agent");
;       xb_add(&bar[XB_XGEN(x)], 1u);
;       asm volatile("s_waitcnt vmcnt(0)" ::: "memory");
;     } else {
;       XB_SPIN(xb_ld(&bar[XB_XGEN(x)]) == k);
;       __builtin_amdgcn_fence(__ATOMIC_ACQUIRE, "agent");
;       asm volatile("s_waitcnt vmcnt(0)" ::: "memory");
;     }
;   }
;   __syncthreads();
; }
.Llb7_done:
	buffer_inv sc1
	s_waitcnt vmcnt(0)
.LBB0_1216:
	s_or_b64 exec, exec, s[4:5]
	s_mov_b32 s33, s0
	s_barrier

; #define LAS __attribute__((address_space(3)))
; __device__ __forceinline__ unsigned xb_ld(unsigned* p)              { return __hip_atomic_load(p, __ATOMIC_RELAXED, __HIP_MEMORY_SCOPE_AGENT); }
; __device__ __forceinline__ unsigned xb_add(unsigned* p, unsigned v) { return __hip_atomic_fetch_add(p, v, __ATOMIC_RELAXED, __HIP_MEMORY_SCOPE_AGENT); }
; #define XB_SPIN(cond) do { unsigned _sp = 0; while (cond) { __builtin_amdgcn_s_sleep(1); if (++_sp > (1u << 24)) break; } } while (0)
; __device__ __forceinline__ void grid_barrier(unsigned* bar, volatile LAS unsigned* st, unsigned k) {
;   asm volatile("s_waitcnt vmcnt(0)" ::: "memory");
;   __syncthreads();
;   if (threadIdx.x == 0) {
;     __builtin_amdgcn_s_waitcnt(0);
;     const unsigned nloc = st[0], nx = st[1], x = st[2];
;     const unsigned old = xb_add(&bar[XB_XSUB(x)], 1u);
;     if (old + 1u == (k + 1u) * nloc) {
;       __builtin_amdgcn_fence(__ATOMIC_RELEASE, "agent");
;       asm volatile("s_waitcnt vmcnt(0)" ::: "memory");
;       const unsigned og = xb_add(&bar[XB_TOP], 1u);
;       if (og + 1u == (k + 1u) * nx) xb_add(&bar[XB_TOPGEN], 1u);
;       else XB_SPIN(xb_ld(&bar[XB_TOPGEN]) == k);
;       __builtin_amdgcn_fence(__ATOMIC_ACQUIRE, "agent");
;       xb_add(&bar[XB_XGEN(x)], 1u);
;       asm volatile("s_waitcnt vmcnt(0)" ::: "memory");
;     } else {
;       XB_SPIN(xb_ld(&bar[XB_XGEN(x)]) == k);
;       __builtin_amdgcn_fence(__ATOMIC_ACQUIRE, "agent");
;       asm volatile("s_waitcnt vmcnt(0)" ::: "memory");
;     }
;   }
;   __syncthreads();
; }
.LBB0_1362:
	s_cmp_lt_i32 s75, 16
	s_cbranch_scc1 .LBB0_1406
	s_waitcnt vmcnt(0)
	s_add_i32 s0, s33, 1
	s_waitcnt vmcnt(0) lgkmcnt(0)
	s_barrier
	s_mov_b64 s[4:5], exec
	v_readlane_b32 s6, v253, 0
	v_readlane_b32 s7, v253, 1
	s_and_b64 s[6:7], s[4:5], s[6:7]
	s_mov_b64 exec, s[6:7]
	s_cbranch_execz .LBB0_1405
	v_mov_b32_e32 v0, 0x20100
	ds_read_b32 v1, v0
	ds_read_b32 v2, v0 offset:4
	ds_read_b32 v3, v0 offset:8
	s_add_u32 s6, s72, 0x19009800
	s_addc_u32 s7, s73, 0
	v_mov_b32_e32 v0, 0
	v_mov_b32_e32 v4, 1
	s_add_i32 s8, s33, 1
	s_waitcnt vmcnt(0) lgkmcnt(0)
	v_readfirstlane_b32 s9, v1
	v_readfirstlane_b32 s10, v2
	v_readfirstlane_b32 vcc_lo, v3
	s_mul_i32 s9, s9, s8
	s_mul_i32 s10, s10, s8
	s_lshl_b32 s8, vcc_lo, 8
	s_add_u32 s6, s6, s8
	s_addc_u32 s7, s7, 0
	global_atomic_add v1, v0, v4, s[6:7] sc0
	s_add_u32 s6, s72, 0x1900b800
	s_addc_u32 s7, s73, 0
	s_mov_b32 vcc_lo, 0
	s_waitcnt vmcnt(0)
	v_readfirstlane_b32 s8, v1
	s_add_i32 s8, s8, 1
	s_cmp_lg_u32 s8, s9
	s_cbranch_scc1 .Llb8_spin
	buffer_wbl2 sc1
	s_waitcnt vmcnt(0)
	global_atomic_add v0, v4, s[6:7]

; #define LAS __attribute__((address_space(3)))
; __device__ __forceinline__ unsigned xb_ld(unsigned* p)              { return __hip_atomic_load(p, __ATOMIC_RELAXED, __HIP_MEMORY_SCOPE_AGENT); }
; __device__ __forceinline__ unsigned xb_add(unsigned* p, unsigned v) { return __hip_atomic_fetch_add(p, v, __ATOMIC_RELAXED, __HIP_MEMORY_SCOPE_AGENT); }
; #define XB_SPIN(cond) do { unsigned _sp = 0; while (cond) { __builtin_amdgcn_s_sleep(1); if (++_sp > (1u << 24)) break; } } while (0)
; __device__ __forceinline__ void grid_barrier(unsigned* bar, volatile LAS unsigned* st, unsigned k) {
;   asm volatile("s_waitcnt vmcnt(0)" ::: "memory");
;   __syncthreads();
;   if (threadIdx.x == 0) {
;     __builtin_amdgcn_s_waitcnt(0);
;     const unsigned nloc = st[0], nx = st[1], x = st[2];
;     const unsigned old = xb_add(&bar[XB_XSUB(x)], 1u);
;     if (old + 1u == (k + 1u) * nloc) {
;       __builtin_amdgcn_fence(__ATOMIC_RELEASE, "agent");
;       asm volatile("s_waitcnt vmcnt(0)" ::: "memory");
;       const unsigned og = xb_add(&bar[XB_TOP], 1u);
;       if (og + 1u == (k + 1u) * nx) xb_add(&bar[XB_TOPGEN], 1u);
;       else XB_SPIN(xb_ld(&bar[XB_TOPGEN]) == k);
;       __builtin_amdgcn_fence(__ATOMIC_ACQUIRE, "agent");
;       xb_add(&bar[XB_XGEN(x)], 1u);
;       asm volatile("s_waitcnt vmcnt(0)" ::: "memory");
;     } else {
;       XB_SPIN(xb_ld(&bar[XB_XGEN(x)]) == k);
;       __builtin_amdgcn_fence(__ATOMIC_ACQUIRE, "agent");
;       asm volatile("s_waitcnt vmcnt(0)" ::: "memory");
;     }
;   }
;   __syncthreads();
; }
.Llb8_done:
	buffer_inv sc1
	s_waitcnt vmcnt(0)
.LBB0_1405:
	s_or_b64 exec, exec, s[4:5]
	s_mov_b32 s33, s0
	s_barrier

; #define LAS __attribute__((address_space(3)))
; __device__ __forceinline__ unsigned xb_ld(unsigned* p)              { return __hip_atomic_load(p, __ATOMIC_RELAXED, __HIP_MEMORY_SCOPE_AGENT); }
; __device__ __forceinline__ unsigned xb_add(unsigned* p, unsigned v) { return __hip_atomic_fetch_add(p, v, __ATOMIC_RELAXED, __HIP_MEMORY_SCOPE_AGENT); }
; #define XB_SPIN(cond) do { unsigned _sp = 0; while (cond) { __builtin_amdgcn_s_sleep(1); if (++_sp > (1u << 24)) break; } } while (0)
; __device__ __forceinline__ void grid_barrier(unsigned* bar, volatile LAS unsigned* st, unsigned k) {
;   asm volatile("s_waitcnt vmcnt(0)" ::: "memory");
;   __syncthreads();
;   if (threadIdx.x == 0) {
;     __builtin_amdgcn_s_waitcnt(0);
;     const unsigned nloc = st[0], nx = st[1], x = st[2];
;     const unsigned old = xb_add(&bar[XB_XSUB(x)], 1u);
;     if (old + 1u == (k + 1u) * nloc) {
;       __builtin_amdgcn_fence(__ATOMIC_RELEASE, "agent");
;       asm volatile("s_waitcnt vmcnt(0)" ::: "memory");
;       const unsigned og = xb_add(&bar[XB_TOP], 1u);
;       if (og + 1u == (k + 1u) * nx) xb_add(&bar[XB_TOPGEN], 1u);
;       else XB_SPIN(xb_ld(&bar[XB_TOPGEN]) == k);
;       __builtin_amdgcn_fence(__ATOMIC_ACQUIRE, "agent");
;       xb_add(&bar[XB_XGEN(x)], 1u);
;       asm volatile("s_waitcnt vmcnt(0)" ::: "memory");
;     } else {
;       XB_SPIN(xb_ld(&bar[XB_XGEN(x)]) == k);
;       __builtin_amdgcn_fence(__ATOMIC_ACQUIRE, "agent");
;       asm volatile("s_waitcnt vmcnt(0)" ::: "memory");
;     }
;   }
;   __syncthreads();
; }
.Llb9_done:
	buffer_inv sc1
	s_waitcnt vmcnt(0)
.LBB0_1488:
	s_or_b64 exec, exec, s[4:5]
	s_mov_b32 s33, s0
	s_barrier

; #define LAS __attribute__((address_space(3)))
; __device__ __forceinline__ unsigned xb_ld(unsigned* p)              { return __hip_atomic_load(p, __ATOMIC_RELAXED, __HIP_MEMORY_SCOPE_AGENT); }
; __device__ __forceinline__ unsigned xb_add(unsigned* p, unsigned v) { return __hip_atomic_fetch_add(p, v, __ATOMIC_RELAXED, __HIP_MEMORY_SCOPE_AGENT); }
; #define XB_SPIN(cond) do { unsigned _sp = 0; while (cond) { __builtin_amdgcn_s_sleep(1); if (++_sp > (1u << 24)) break; } } while (0)
; __device__ __forceinline__ void grid_barrier(unsigned* bar, volatile LAS unsigned* st, unsigned k) {
;   asm volatile("s_waitcnt vmcnt(0)" ::: "memory");
;   __syncthreads();
;   if (threadIdx.x == 0) {
;     __builtin_amdgcn_s_waitcnt(0);
;     const unsigned nloc = st[0], nx = st[1], x = st[2];
;     const unsigned old = xb_add(&bar[XB_XSUB(x)], 1u);
;     if (old + 1u == (k + 1u) * nloc) {
;       __builtin_amdgcn_fence(__ATOMIC_RELEASE, "agent");
;       asm volatile("s_waitcnt vmcnt(0)" ::: "memory");
;       const unsigned og = xb_add(&bar[XB_TOP], 1u);
;       if (og + 1u == (k + 1u) * nx) xb_add(&bar[XB_TOPGEN], 1u);
;       else XB_SPIN(xb_ld(&bar[XB_TOPGEN]) == k);
;       __builtin_amdgcn_fence(__ATOMIC_ACQUIRE, "agent");
;       xb_add(&bar[XB_XGEN(x)], 1u);
;       asm volatile("s_waitcnt vmcnt(0)" ::: "memory");
;     } else {
;       XB_SPIN(xb_ld(&bar[XB_XGEN(x)]) == k);
;       __builtin_amdgcn_fence(__ATOMIC_ACQUIRE, "agent");
;       asm volatile("s_waitcnt vmcnt(0)" ::: "memory");
;     }
;   }
;   __syncthreads();
; }
.Llb10_done:
	buffer_inv sc1
	s_waitcnt vmcnt(0)
.LBB0_1579:
	s_or_b64 exec, exec, s[4:5]
	s_mov_b32 s33, s0
	s_barrier

; #define LAS __attribute__((address_space(3)))
; __device__ __forceinline__ unsigned xb_ld(unsigned* p)              { return __hip_atomic_load(p, __ATOMIC_RELAXED, __HIP_MEMORY_SCOPE_AGENT); }
; __device__ __forceinline__ unsigned xb_add(unsigned* p, unsigned v) { return __hip_atomic_fetch_add(p, v, __ATOMIC_RELAXED, __HIP_MEMORY_SCOPE_AGENT); }
; #define XB_SPIN(cond) do { unsigned _sp = 0; while (cond) { __builtin_amdgcn_s_sleep(1); if (++_sp > (1u << 24)) break; } } while (0)
; __device__ __forceinline__ void grid_barrier(unsigned* bar, volatile LAS unsigned* st, unsigned k) {
;   asm volatile("s_waitcnt vmcnt(0)" ::: "memory");
;   __syncthreads();
;   if (threadIdx.x == 0) {
;     __builtin_amdgcn_s_waitcnt(0);
;     const unsigned nloc = st[0], nx = st[1], x = st[2];
;     const unsigned old = xb_add(&bar[XB_XSUB(x)], 1u);
;     if (old + 1u == (k + 1u) * nloc) {
;       __builtin_amdgcn_fence(__ATOMIC_RELEASE, "agent");
;       asm volatile("s_waitcnt vmcnt(0)" ::: "memory");
;       const unsigned og = xb_add(&bar[XB_TOP], 1u);
;       if (og + 1u == (k + 1u) * nx) xb_add(&bar[XB_TOPGEN], 1u);
;       else XB_SPIN(xb_ld(&bar[XB_TOPGEN]) == k);
;       __builtin_amdgcn_fence(__ATOMIC_ACQUIRE, "agent");
;       xb_add(&bar[XB_XGEN(x)], 1u);
;       asm volatile("s_waitcnt vmcnt(0)" ::: "memory");
;     } else {
;       XB_SPIN(xb_ld(&bar[XB_XGEN(x)]) == k);
;       __builtin_amdgcn_fence(__ATOMIC_ACQUIRE, "agent");
;       asm volatile("s_waitcnt vmcnt(0)" ::: "memory");
;     }
;   }
;   __syncthreads();
; }
.LBB0_1584:
	s_or_b64 exec, exec, s[10:11]
	v_readlane_b32 s56, v253, 20
	s_cmp_lt_u32 s75, 20
	v_readlane_b32 s57, v253, 21
	s_cbranch_scc1 .LBB0_1629
	s_waitcnt vmcnt(0)
	s_add_i32 s0, s33, 1
	s_waitcnt vmcnt(0) lgkmcnt(0)
	s_barrier
	s_mov_b64 s[4:5], exec
	v_readlane_b32 s6, v253, 0
	v_readlane_b32 s7, v253, 1
	s_and_b64 s[6:7], s[4:5], s[6:7]
	s_mov_b64 exec, s[6:7]
	s_cbranch_execz .LBB0_1628
	v_mov_b32_e32 v0, 0x20100
	ds_read_b32 v1, v0
	ds_read_b32 v2, v0 offset:4
	ds_read_b32 v3, v0 offset:8
	s_add_u32 s6, s72, 0x19009800
	s_addc_u32 s7, s73, 0
	v_mov_b32_e32 v0, 0
	v_mov_b32_e32 v4, 1
	s_add_i32 s8, s33, 1
	s_waitcnt vmcnt(0) lgkmcnt(0)
	v_readfirstlane_b32 s9, v1
	v_readfirstlane_b32 s10, v2
	v_readfirstlane_b32 vcc_lo, v3
	s_mul_i32 s9, s9, s8
	s_mul_i32 s10, s10, s8
	s_lshl_b32 s8, vcc_lo, 8
	s_add_u32 s6, s6, s8
	s_addc_u32 s7, s7, 0
	global_atomic_add v1, v0, v4, s[6:7] sc0
	s_add_u32 s6, s72, 0x1900b800
	s_addc_u32 s7, s73, 0
	s_mov_b32 vcc_lo, 0
	s_waitcnt vmcnt(0)
	v_readfirstlane_b32 s8, v1
	s_add_i32 s8, s8, 1
	s_cmp_lg_u32 s8, s9
	s_cbranch_scc1 .Llb11_spin
	buffer_wbl2 sc1
	s_waitcnt vmcnt(0)
	global_atomic_add v0, v4, s[6:7]

; #define LAS __attribute__((address_space(3)))
; __device__ __forceinline__ unsigned xb_ld(unsigned* p)              { return __hip_atomic_load(p, __ATOMIC_RELAXED, __HIP_MEMORY_SCOPE_AGENT); }
; __device__ __forceinline__ unsigned xb_add(unsigned* p, unsigned v) { return __hip_atomic_fetch_add(p, v, __ATOMIC_RELAXED, __HIP_MEMORY_SCOPE_AGENT); }
; #define XB_SPIN(cond) do { unsigned _sp = 0; while (cond) { __builtin_amdgcn_s_sleep(1); if (++_sp > (1u << 24)) break; } } while (0)
; __device__ __forceinline__ void grid_barrier(unsigned* bar, volatile LAS unsigned* st, unsigned k) {
;   asm volatile("s_waitcnt vmcnt(0)" ::: "memory");
;   __syncthreads();
;   if (threadIdx.x == 0) {
;     __builtin_amdgcn_s_waitcnt(0);
;     const unsigned nloc = st[0], nx = st[1], x = st[2];
;     const unsigned old = xb_add(&bar[XB_XSUB(x)], 1u);
;     if (old + 1u == (k + 1u) * nloc) {
;       __builtin_amdgcn_fence(__ATOMIC_RELEASE, "agent");
;       asm volatile("s_waitcnt vmcnt(0)" ::: "memory");
;       const unsigned og = xb_add(&bar[XB_TOP], 1u);
;       if (og + 1u == (k + 1u) * nx) xb_add(&bar[XB_TOPGEN], 1u);
;       else XB_SPIN(xb_ld(&bar[XB_TOPGEN]) == k);
;       __builtin_amdgcn_fence(__ATOMIC_ACQUIRE, "agent");
;       xb_add(&bar[XB_XGEN(x)], 1u);
;       asm volatile("s_waitcnt vmcnt(0)" ::: "memory");
;     } else {
;       XB_SPIN(xb_ld(&bar[XB_XGEN(x)]) == k);
;       __builtin_amdgcn_fence(__ATOMIC_ACQUIRE, "agent");
;       asm volatile("s_waitcnt vmcnt(0)" ::: "memory");
;     }
;   }
;   __syncthreads();
; }
.LBB0_1590:
	v_readlane_b32 s56, v253, 20
	v_readlane_b32 s57, v253, 21
	s_branch .LBB0_1629
.LBB0_1628:
	s_or_b64 exec, exec, s[4:5]
	s_barrier
	s_mov_b32 s33, s0

; #define LAS __attribute__((address_space(3)))
; __device__ __forceinline__ unsigned xb_ld(unsigned* p)              { return __hip_atomic_load(p, __ATOMIC_RELAXED, __HIP_MEMORY_SCOPE_AGENT); }
; __device__ __forceinline__ unsigned xb_add(unsigned* p, unsigned v) { return __hip_atomic_fetch_add(p, v, __ATOMIC_RELAXED, __HIP_MEMORY_SCOPE_AGENT); }
; #define XB_SPIN(cond) do { unsigned _sp = 0; while (cond) { __builtin_amdgcn_s_sleep(1); if (++_sp > (1u << 24)) break; } } while (0)
; __device__ __forceinline__ void grid_barrier(unsigned* bar, volatile LAS unsigned* st, unsigned k) {
;   asm volatile("s_waitcnt vmcnt(0)" ::: "memory");
;   __syncthreads();
;   if (threadIdx.x == 0) {
;     __builtin_amdgcn_s_waitcnt(0);
;     const unsigned nloc = st[0], nx = st[1], x = st[2];
;     const unsigned old = xb_add(&bar[XB_XSUB(x)], 1u);
;     if (old + 1u == (k + 1u) * nloc) {
;       __builtin_amdgcn_fence(__ATOMIC_RELEASE, "agent");
;       asm volatile("s_waitcnt vmcnt(0)" ::: "memory");
;       const unsigned og = xb_add(&bar[XB_TOP], 1u);
;       if (og + 1u == (k + 1u) * nx) xb_add(&bar[XB_TOPGEN], 1u);
;       else XB_SPIN(xb_ld(&bar[XB_TOPGEN]) == k);
;       __builtin_amdgcn_fence(__ATOMIC_ACQUIRE, "agent");
;       xb_add(&bar[XB_XGEN(x)], 1u);
;       asm volatile("s_waitcnt vmcnt(0)" ::: "memory");
;     } else {
;       XB_SPIN(xb_ld(&bar[XB_XGEN(x)]) == k);
;       __builtin_amdgcn_fence(__ATOMIC_ACQUIRE, "agent");
;       asm volatile("s_waitcnt vmcnt(0)" ::: "memory");
;     }
;   }
;   __syncthreads();
; }
.LBB0_1674:
	s_waitcnt vmcnt(0)
	s_add_i32 s3, s33, 1
	s_waitcnt vmcnt(0) lgkmcnt(0)
	s_barrier
	s_mov_b64 s[4:5], exec
	v_readlane_b32 s0, v253, 0
	v_readlane_b32 s1, v253, 1
	v_readlane_b32 s16, v253, 32
	s_and_b64 s[0:1], s[4:5], s[0:1]
	v_readlane_b32 s20, v253, 36
	v_readlane_b32 s21, v253, 37
	v_readlane_b32 s22, v253, 38
	v_readlane_b32 s23, v253, 39
	v_readlane_b32 s17, v253, 33
	v_readlane_b32 s18, v253, 34
	v_readlane_b32 s19, v253, 35
	s_mov_b64 exec, s[0:1]
	s_cbranch_execz .LBB0_1716
	v_mov_b32_e32 v0, 0x20100
	ds_read_b32 v1, v0
	ds_read_b32 v2, v0 offset:4
	ds_read_b32 v3, v0 offset:8
	s_add_u32 s6, s72, 0x19009800
	s_addc_u32 s7, s73, 0
	v_mov_b32_e32 v0, 0
	v_mov_b32_e32 v4, 1
	s_add_i32 s8, s33, 1
	s_waitcnt vmcnt(0) lgkmcnt(0)
	v_readfirstlane_b32 s9, v1
	v_readfirstlane_b32 s10, v2
	v_readfirstlane_b32 vcc_lo, v3
	s_mul_i32 s9, s9, s8
	s_mul_i32 s10, s10, s8
	s_lshl_b32 s8, vcc_lo, 8
	s_add_u32 s6, s6, s8
	s_addc_u32 s7, s7, 0
	global_atomic_add v1, v0, v4, s[6:7] sc0
	s_add_u32 s6, s72, 0x1900b800
	s_addc_u32 s7, s73, 0
	s_mov_b32 vcc_lo, 0
	s_waitcnt vmcnt(0)
	v_readfirstlane_b32 s8, v1
	s_add_i32 s8, s8, 1
	s_cmp_lg_u32 s8, s9
	s_cbranch_scc1 .Llb12_spin
	buffer_wbl2 sc1
	s_waitcnt vmcnt(0)
	global_atomic_add v0, v4, s[6:7]

; #define LAS __attribute__((address_space(3)))
; __device__ __forceinline__ unsigned xb_ld(unsigned* p)              { return __hip_atomic_load(p, __ATOMIC_RELAXED, __HIP_MEMORY_SCOPE_AGENT); }
; __device__ __forceinline__ unsigned xb_add(unsigned* p, unsigned v) { return __hip_atomic_fetch_add(p, v, __ATOMIC_RELAXED, __HIP_MEMORY_SCOPE_AGENT); }
; #define XB_SPIN(cond) do { unsigned _sp = 0; while (cond) { __builtin_amdgcn_s_sleep(1); if (++_sp > (1u << 24)) break; } } while (0)
; __device__ __forceinline__ void grid_barrier(unsigned* bar, volatile LAS unsigned* st, unsigned k) {
;   asm volatile("s_waitcnt vmcnt(0)" ::: "memory");
;   __syncthreads();
;   if (threadIdx.x == 0) {
;     __builtin_amdgcn_s_waitcnt(0);
;     const unsigned nloc = st[0], nx = st[1], x = st[2];
;     const unsigned old = xb_add(&bar[XB_XSUB(x)], 1u);
;     if (old + 1u == (k + 1u) * nloc) {
;       __builtin_amdgcn_fence(__ATOMIC_RELEASE, "agent");
;       asm volatile("s_waitcnt vmcnt(0)" ::: "memory");
;       const unsigned og = xb_add(&bar[XB_TOP], 1u);
;       if (og + 1u == (k + 1u) * nx) xb_add(&bar[XB_TOPGEN], 1u);
;       else XB_SPIN(xb_ld(&bar[XB_TOPGEN]) == k);
;       __builtin_amdgcn_fence(__ATOMIC_ACQUIRE, "agent");
;       xb_add(&bar[XB_XGEN(x)], 1u);
;       asm volatile("s_waitcnt vmcnt(0)" ::: "memory");
;     } else {
;       XB_SPIN(xb_ld(&bar[XB_XGEN(x)]) == k);
;       __builtin_amdgcn_fence(__ATOMIC_ACQUIRE, "agent");
;       asm volatile("s_waitcnt vmcnt(0)" ::: "memory");
;     }
;   }
;   __syncthreads();
; }
.Llb12_done:
	buffer_inv sc1
	s_waitcnt vmcnt(0)
.LBB0_1716:
	s_or_b64 exec, exec, s[4:5]
	s_barrier
	s_mov_b32 s33, s3
